# v21 + attention K/V staging no longer waits for the next round's Q loads (counted vmcnt on the loop back-edge path, both attention phases)
# speedup vs baseline: 1.0284x; 1.0088x over previous
; #define LAS __attribute__((address_space(3)))
; __device__ __forceinline__ void attn_stage(LAS unsigned char* lds, const u32x4 (&kv)[6], const u32x4 (&vv)[6], int tid, int wid) {
;     LAS unsigned char* Kl = lds; LAS unsigned char* Vl = lds + 49152;
; #pragma unroll
;     for (int c = 0; c < 6; ++c) { const int idx = tid + 512 * c, j = idx >> 3, ch = idx & 7;
;         *(LAS u32x4*)(Kl + j * 128 + ((ch ^ ((j >> 1) & 7)) * 16)) = kv[c];
;         *(LAS u32x4*)(Vl + j * 128 + (((ch >> 2) ^ ((j >> 1) & 1)) * 64) + (ch & 3) * 16) = vv[c]; }
; }
; template <bool FINAL>
; __device__ __forceinline__ void attn_compute(LAS unsigned char* lds, const bf16_t* proj, const AttnItem& t, const AttnItem& nxt, bool more, bf16x8 (&qf)[4], bf16_t* o23, float* lse23, bf16_t* ycat, int lane, int wid) {
;     ...
;         const float c1 = 1.0f / l;
;         if (hi == 0) lse23[(size_t)t.br * M * NH + hrow] = lse;
;         bf16_t* ob = o23 + ((size_t)t.br * M * NH + hrow) * HD + 8 * hi;
; #pragma unroll
;         for (int d = 0; d < 2; ++d)
; #pragma unroll
;             for (int g = 0; g < 4; g += 2) { u32x2 wa, wb;
;                 wa.x = cvt_pk_bf16(o[d][4 * g] * c1, o[d][4 * g + 1] * c1); wa.y = cvt_pk_bf16(o[d][4 * g + 2] * c1, o[d][4 * g + 3] * c1);
;                 wb.x = cvt_pk_bf16(o[d][4 * g + 4] * c1, o[d][4 * g + 5] * c1); wb.y = cvt_pk_bf16(o[d][4 * g + 6] * c1, o[d][4 * g + 7] * c1);
;                 *(u32x4*)(ob + 32 * d + 8 * g) = pair16(wa, wb); }
.LBB0_107:
	s_or_b64 exec, exec, s[2:3]
	v_div_scale_f32 v34, s[2:3], v35, v35, 1.0
	v_rcp_f32_e32 v36, v34
	v_lshlrev_b64 v[32:33], 25, v[32:33]
	v_lshl_add_u64 v[32:33], s[42:43], 0, v[32:33]
	s_and_b64 s[2:3], s[46:47], exec
	v_fma_f32 v37, -v34, v36, 1.0
	v_fmac_f32_e32 v36, v37, v36
	v_div_scale_f32 v37, vcc, 1.0, v35, 1.0
	v_mul_f32_e32 v38, v37, v36
	v_fma_f32 v39, -v34, v38, v37
	v_fmac_f32_e32 v38, v39, v36
	v_fma_f32 v34, -v34, v38, v37
	v_div_fmas_f32 v34, v34, v36, v38
	v_div_fixup_f32 v34, v34, v35, 1.0
	v_pk_mul_f32 v[16:17], v[16:17], v[34:35] op_sel_hi:[1,0]
	v_pk_mul_f32 v[18:19], v[18:19], v[34:35] op_sel_hi:[1,0]
	v_pk_mul_f32 v[0:1], v[0:1], v[34:35] op_sel_hi:[1,0]
	v_pk_mul_f32 v[2:3], v[2:3], v[34:35] op_sel_hi:[1,0]
	v_lshlrev_b64 v[36:37], 7, v[168:169]
	v_cvt_pk_bf16_f32 v16, v16, v17
	v_cvt_pk_bf16_f32 v17, v18, v19
	v_pk_mul_f32 v[18:19], v[20:21], v[34:35] op_sel_hi:[1,0]
	v_pk_mul_f32 v[20:21], v[22:23], v[34:35] op_sel_hi:[1,0]
	v_cvt_pk_bf16_f32 v0, v0, v1
	v_cvt_pk_bf16_f32 v1, v2, v3
	v_pk_mul_f32 v[2:3], v[4:5], v[34:35] op_sel_hi:[1,0]
	v_pk_mul_f32 v[4:5], v[6:7], v[34:35] op_sel_hi:[1,0]
	v_lshl_add_u64 v[32:33], v[32:33], 0, v[36:37]
	v_cvt_pk_bf16_f32 v18, v18, v19
	v_cvt_pk_bf16_f32 v19, v20, v21
	v_cvt_pk_bf16_f32 v2, v2, v3
	v_cvt_pk_bf16_f32 v3, v4, v5
	v_lshl_add_u64 v[32:33], v[128:129], 1, v[32:33]
	v_permlane32_swap_b32_e32 v16, v18
	v_permlane32_swap_b32_e32 v17, v19
	v_permlane32_swap_b32_e32 v0, v2
	v_permlane32_swap_b32_e32 v1, v3
	global_store_dwordx4 v[32:33], v[16:19], off
	global_store_dwordx4 v[32:33], v[0:3], off offset:64
	v_pk_mul_f32 v[20:21], v[30:31], v[34:35] op_sel_hi:[1,0]
	v_pk_mul_f32 v[16:17], v[24:25], v[34:35] op_sel_hi:[1,0]
	v_pk_mul_f32 v[18:19], v[26:27], v[34:35] op_sel_hi:[1,0]
	v_pk_mul_f32 v[0:1], v[8:9], v[34:35] op_sel_hi:[1,0]
	v_pk_mul_f32 v[2:3], v[10:11], v[34:35] op_sel_hi:[1,0]
	v_cvt_pk_bf16_f32 v16, v16, v17
	v_cvt_pk_bf16_f32 v17, v18, v19
	v_pk_mul_f32 v[18:19], v[28:29], v[34:35] op_sel_hi:[1,0]
	v_cvt_pk_bf16_f32 v0, v0, v1
	v_cvt_pk_bf16_f32 v1, v2, v3
	v_pk_mul_f32 v[2:3], v[12:13], v[34:35] op_sel_hi:[1,0]
	v_pk_mul_f32 v[4:5], v[14:15], v[34:35] op_sel_hi:[1,0]
	v_cvt_pk_bf16_f32 v18, v18, v19
	v_cvt_pk_bf16_f32 v19, v20, v21
	v_cvt_pk_bf16_f32 v2, v2, v3
	v_cvt_pk_bf16_f32 v3, v4, v5
	v_permlane32_swap_b32_e32 v16, v18
	v_permlane32_swap_b32_e32 v17, v19
	v_permlane32_swap_b32_e32 v0, v2
	v_permlane32_swap_b32_e32 v1, v3
	global_store_dwordx4 v[32:33], v[16:19], off offset:32
	global_store_dwordx4 v[32:33], v[0:3], off offset:96
	s_waitcnt lgkmcnt(0)
	s_barrier
	s_cselect_b32 s20, 4, 16
	s_cmp_eq_u32 s17, s21
	s_mov_b32 s25, s15
	s_mov_b32 s24, s98
	s_mov_b32 s22, s11
	s_mov_b32 s23, s99
	s_cbranch_scc1 .LBB0_116
	s_waitcnt vmcnt(20)
	ds_write_b128 v151, v[64:67]
	s_waitcnt vmcnt(19)
	ds_write_b128 v152, v[68:71] offset:49152
	s_waitcnt vmcnt(18)
	ds_write_b128 v153, v[72:75]
	s_waitcnt vmcnt(17)
	ds_write_b128 v154, v[76:79] offset:49152
	s_waitcnt vmcnt(16)
	ds_write_b128 v155, v[80:83]
	s_waitcnt vmcnt(15)
	ds_write_b128 v156, v[84:87] offset:49152
	s_waitcnt vmcnt(14)
	ds_write_b128 v157, v[88:91]
	s_waitcnt vmcnt(13)
	ds_write_b128 v158, v[92:95] offset:49152
	s_waitcnt vmcnt(12)
	ds_write_b128 v159, v[96:99]
	s_waitcnt vmcnt(11)
	ds_write_b128 v160, v[100:103] offset:49152
	s_waitcnt vmcnt(10)
	ds_write_b128 v161, v[104:107]
	s_waitcnt vmcnt(9)
	ds_write_b128 v162, v[108:111] offset:49152
	s_branch .Lattn_a_ldone

; template <bool FINAL>
; __device__ __forceinline__ void attn_phase(LAS unsigned char* lds, const bf16_t* proj, bf16_t* o23, float* lse23, bf16_t* ycat, int tid, int lane, int wid) {
;     ...
;     const int SPB = affine ? RB / J : 1, NS = affine ? 4 * SPB : (NR - (int)blockIdx.x + G - 1) / G;
;     auto round_of = [&](int t) -> int {
;         if (!affine) return (int)blockIdx.x + t * G;
;         const int sidx = t / SPB, rr = jj + J * (t % SPB), bh = 4 * xcd + sidx;
;         return FINAL ? bh * 32 + rr : (rr >> 5) * 1024 + bh * 32 + (rr & 31); };
;     ...
;         asm volatile("s_waitcnt lgkmcnt(0)\n\ts_barrier" ::: "memory");
;         const bool more = t + 1 < NS;
;         const AttnItem nxt = attn_decode<FINAL>(round_of(more ? t + 1 : t), wid);
.Lattn_a_ldone:
	s_mov_b32 s2, s21
	s_waitcnt lgkmcnt(0)
	s_barrier
	s_add_i32 s21, s21, 1
	s_cmp_lt_i32 s21, s17
	s_cselect_b32 s6, s21, s2
	s_andn2_b64 vcc, exec, s[44:45]
	s_mov_b64 s[2:3], -1
	s_cbranch_vccnz .LBB0_110
	s_mul_i32 s2, s6, s30
	v_readlane_b32 s3, v251, 42
	s_add_i32 s7, s2, s3
	s_mov_b64 s[2:3], 0

; #define LAS __attribute__((address_space(3)))
; __device__ __forceinline__ int tpos(int t) { return (t & ~2047) | ((t & 15) << 7) | ((t & 2047) >> 4); }
; template <bool FINAL> __device__ __forceinline__ AttnItem attn_decode(int R, int wid) {
;     AttnItem t; const int it = 2 * R + (wid >> 2);
;     if (!FINAL) { const int br = it >> 11, rem = it & 2047, bh = rem >> 6, rn = rem & 63; t.br = br; t.dil = br ? 16 : 4; const int nbc = 64 / t.dil; t.r = rn / nbc; t.nb = rn % nbc; t.b = bh >> 3; t.h = bh & 7; }
;     else { const int bh = it >> 6; t.br = 0; t.dil = 1; t.r = 0; t.nb = it & 63; t.b = bh >> 3; t.h = bh & 7; }
;     return t;
; }
; __device__ __forceinline__ void attn_load(const bf16_t* proj, const AttnItem& t, u32x4 (&kv)[6], u32x4 (&vv)[6], int tid) {
;     const int nb0 = t.nb & ~1;
;     const bf16_t* kb = proj + (size_t)NB * NH * SEQ * HD + (size_t)(t.b * NH + t.h) * SEQ * 2 * HD;
; #pragma unroll
;     for (int c = 0; c < 6; ++c) { const int idx = tid + 512 * c, j = idx >> 3, ch = idx & 7; const int sidx = (nb0 - 1) * 128 + j;
;         const int sj = sidx >= 0 ? sidx : sidx + 128;
;         const bf16_t* p = kb + (size_t)tpos(sj * t.dil + t.r) * 2 * HD + ch * 8; kv[c] = *(const u32x4*)p; vv[c] = *(const u32x4*)(p + HD); }
; template <int T0, int NT, bool FIRST>
; __device__ __forceinline__ void attn_group(LAS const unsigned char* Kl, LAS const unsigned char* Vl, const bf16x8 (&qf)[4], f32x16 (&o)[2], float& mx, float& l, int nb, int w, int lane) {
;     const int r32 = lane & 31, hi = lane >> 5;
;     f32x16 s[NT];
; #pragma unroll
;     for (int t = 0; t < NT; ++t) { const float z = (T0 + t < 4 && nb == 0 && w + T0 + t < 4) ? NEGBIG : 0.f;
;         s[t] = (f32x16){z, z, z, z, z, z, z, z, z, z, z, z, z, z, z, z}; }
;     {
;         LAS const unsigned char* kp = Kl + (32 * (w + T0) + r32) * 128;
;         const int sw = (r32 >> 1) & 7;
; #pragma unroll
;         for (int ks = 0; ks < 4; ++ks) {
;             bf16x8 kf[NT];
; #pragma unroll
;             for (int t = 0; t < NT; ++t) kf[t] = *(LAS const bf16x8*)(kp + t * 4096 + (((2 * ks + hi) ^ sw) * 16));
; #pragma unroll
;             for (int t = 0; t < NT; ++t) s[t] = __builtin_amdgcn_mfma_f32_32x32x16_bf16(kf[t], qf[ks], s[t], 0, 0, 0);
.LBB0_474:
	s_lshl_b32 s10, s14, 1
	s_add_i32 s10, s10, s16
	s_ashr_i32 s20, s10, 9
	s_bfe_u32 s21, s10, 0x30006
	s_lshl_b32 s14, s20, 3
	s_and_b32 s22, s10, 63
	s_or_b32 s24, s14, s21
	s_lshl_b32 s14, s22, 7
	s_and_b32 s10, s14, 0x1f00
	s_add_i32 s19, s10, 0xffffff80
	v_add_u32_e32 v0, s19, v138
	v_add_u32_e32 v1, s10, v138
	v_cmp_gt_i32_e32 vcc, 0, v0
	s_ashr_i32 s25, s24, 31
	s_lshl_b64 s[26:27], s[24:25], 21
	v_cndmask_b32_e32 v187, v0, v1, vcc
	v_add_u32_e32 v0, s19, v139
	v_add_u32_e32 v1, s10, v139
	v_cmp_gt_i32_e32 vcc, 0, v0
	v_add_u32_e32 v33, v147, v148
	v_lshl_add_u64 v[88:89], v[98:99], 0, s[26:27]
	v_cndmask_b32_e32 v87, v0, v1, vcc
	v_add_u32_e32 v0, s19, v140
	v_add_u32_e32 v1, s10, v140
	v_cmp_gt_i32_e32 vcc, 0, v0
	ds_read_b128 v[10:13], v33
	ds_read_b128 v[34:37], v33 offset:4096
	v_cndmask_b32_e32 v86, v0, v1, vcc
	v_add_u32_e32 v0, s19, v141
	v_add_u32_e32 v1, s10, v141
	v_cmp_gt_i32_e32 vcc, 0, v0
	s_ashr_i32 s99, s98, 31
	v_readlane_b32 s44, v250, 4
	v_cndmask_b32_e32 v85, v0, v1, vcc
	v_add_u32_e32 v0, s19, v142
	v_add_u32_e32 v1, s10, v142
	v_cmp_gt_i32_e32 vcc, 0, v0
	v_readlane_b32 s45, v250, 5
	v_add_u32_e32 v131, v155, v149
	v_cndmask_b32_e32 v84, v0, v1, vcc
	v_add_u32_e32 v1, s10, v143
	s_lshl_b32 s10, s98, 3
	s_or_b32 s26, s10, s12
	v_add_u32_e32 v0, s19, v143
	s_ashr_i32 s27, s26, 31
	s_lshl_b32 s19, s23, 7
	s_lshl_b64 s[26:27], s[26:27], 13
	s_and_b32 s10, s19, 0x1800
	v_cmp_gt_i32_e32 vcc, 0, v0
	s_cmp_eq_u32 s23, 0
	v_or_b32_e32 v188, s19, v146
	v_cndmask_b32_e32 v186, v0, v1, vcc
	s_cselect_b64 vcc, -1, 0
	v_bfe_u32 v1, v188, 4, 7
	v_cndmask_b32_e32 v32, 0, v227, vcc
	s_and_b64 vcc, vcc, s[44:45]
	s_or_b32 s23, s23, s18
	v_or_b32_e32 v1, s10, v1
	s_cmp_eq_u32 s23, 0
	v_or3_b32 v2, v1, v145, s26
	v_mov_b32_e32 v3, s27
	v_readlane_b32 s26, v251, 61
	v_cndmask_b32_e32 v16, 0, v227, vcc
	s_cselect_b64 vcc, -1, 0
	v_readlane_b32 s27, v251, 62
	v_or_b32_e32 v1, s14, v144
	v_cndmask_b32_e32 v0, 0, v227, vcc
	v_lshl_add_u64 v[82:83], v[2:3], 2, s[26:27]
	v_lshlrev_b64 v[2:3], 7, v[2:3]
	v_lshrrev_b32_e32 v1, 4, v1
	v_mov_b32_e32 v17, v16
	v_mov_b32_e32 v18, v16
	v_mov_b32_e32 v19, v16
	v_mov_b32_e32 v20, v16
	v_mov_b32_e32 v21, v16
	v_mov_b32_e32 v22, v16
	v_mov_b32_e32 v23, v16
	v_mov_b32_e32 v24, v16
	v_mov_b32_e32 v25, v16
	v_mov_b32_e32 v26, v16
	v_mov_b32_e32 v27, v16
	v_mov_b32_e32 v28, v16
	v_mov_b32_e32 v29, v16
	v_mov_b32_e32 v30, v16
	v_mov_b32_e32 v31, v16
	v_lshl_add_u64 v[106:107], v[100:101], 0, v[2:3]
	v_or_b32_e32 v90, s14, v1
	v_mov_b32_e32 v1, v0
	v_mov_b32_e32 v2, v0
	v_mov_b32_e32 v3, v0
	v_mov_b32_e32 v4, v0
	v_mov_b32_e32 v5, v0
	v_mov_b32_e32 v6, v0
	v_mov_b32_e32 v7, v0
	v_mov_b32_e32 v8, v0
	s_waitcnt vmcnt(3) lgkmcnt(1)
	v_mfma_f32_32x32x16_bf16 v[16:31], v[10:13], v[76:79], v[16:31]
	v_mov_b32_e32 v9, v0
	v_mov_b32_e32 v10, v0
	v_mov_b32_e32 v11, v0
	v_mov_b32_e32 v12, v0
	v_mov_b32_e32 v13, v0
	v_mov_b32_e32 v14, v0
	v_mov_b32_e32 v15, v0
	s_mov_b32 s10, 0x100000
	v_add_co_u32_e32 v80, vcc, s10, v82
	s_waitcnt lgkmcnt(0)
	v_mfma_f32_32x32x16_bf16 v[0:15], v[34:37], v[76:79], v[0:15]
	ds_read_b128 v[34:37], v33 offset:8192
	v_add_u32_e32 v33, v147, v149
	ds_read_b128 v[50:53], v33
	v_addc_co_u32_e32 v81, vcc, 0, v83, vcc
	s_brev_b32 s10, 64
	v_add_co_u32_e32 v104, vcc, s10, v106
	s_waitcnt vmcnt(2) lgkmcnt(0)
	v_mfma_f32_32x32x16_bf16 v[16:31], v[50:53], v[72:75], v[16:31]
	ds_read_b128 v[50:53], v33 offset:4096
	v_addc_co_u32_e32 v105, vcc, 0, v107, vcc
	s_lshl_b64 s[24:25], s[24:25], 20
	v_readlane_b32 s26, v251, 59
	v_readlane_b32 s27, v251, 60
	s_add_u32 vcc_lo, s26, s24
	s_waitcnt lgkmcnt(0)
	v_mfma_f32_32x32x16_bf16 v[0:15], v[50:53], v[72:75], v[0:15]
	ds_read_b128 v[50:53], v33 offset:8192
	v_add_u32_e32 v33, v147, v150
	s_addc_u32 vcc_hi, s27, s25
	v_readlane_b32 s24, v250, 6
	v_readlane_b32 s25, v250, 7
	s_movk_i32 s10, 0x187f
	v_readlane_b32 s26, v251, 57
	v_mfma_f32_32x32x16_bf16 v[34:49], v[34:37], v[76:79], 0
	v_readlane_b32 s27, v251, 58
	s_mov_b32 s23, s22
	s_waitcnt lgkmcnt(0)
	v_mfma_f32_32x32x16_bf16 v[34:49], v[50:53], v[72:75], v[34:49]
	ds_read_b128 v[50:53], v33
	s_waitcnt vmcnt(1) lgkmcnt(0)
	v_mfma_f32_32x32x16_bf16 v[16:31], v[50:53], v[68:71], v[16:31]
	ds_read_b128 v[50:53], v33 offset:4096
	s_waitcnt lgkmcnt(0)
	v_mfma_f32_32x32x16_bf16 v[0:15], v[50:53], v[68:71], v[0:15]
	ds_read_b128 v[50:53], v33 offset:8192
	v_add_u32_e32 v33, v147, v151
	s_waitcnt lgkmcnt(0)
	v_mfma_f32_32x32x16_bf16 v[34:49], v[50:53], v[68:71], v[34:49]
	ds_read_b128 v[50:53], v33
	s_waitcnt vmcnt(0) lgkmcnt(0)
	v_mfma_f32_32x32x16_bf16 v[16:31], v[50:53], v[64:67], v[16:31]
	ds_read_b128 v[50:53], v33 offset:4096
	s_waitcnt lgkmcnt(0)
	v_mfma_f32_32x32x16_bf16 v[0:15], v[50:53], v[64:67], v[0:15]
	ds_read_b128 v[50:53], v33 offset:8192
	s_waitcnt lgkmcnt(0)
; __device__ __forceinline__ int crow(int i, int hi) { return (i & 3) + 8 * (i >> 2) + 4 * hi; }
; template <int T0, int NT, bool FIRST>
; __device__ __forceinline__ void attn_group(LAS const unsigned char* Kl, LAS const unsigned char* Vl, const bf16x8 (&qf)[4], f32x16 (&o)[2], float& mx, float& l, int nb, int w, int lane) {
;     ...
; #pragma unroll
;     for (int t = 0; t < NT; ++t) {
;         const int tt = T0 + t;
;         if (tt == 0) {
; #pragma unroll
;             for (int i = 0; i < 16; ++i) if (crow(i, hi) < r32) s[t][i] = NEGBIG; }
;         if (tt == 4) {
; #pragma unroll
;             for (int i = 0; i < 16; ++i) if (crow(i, hi) > r32) s[t][i] = NEGBIG; }
;     }
;     float m0 = s[0][0], m1 = s[0][1], m2 = s[0][2], m3 = s[0][3];
; #pragma unroll
;     for (int t = 0; t < NT; ++t)
; #pragma unroll
;         for (int i = 0; i < 16; i += 4) { m0 = fmaxf(m0, s[t][i]); m1 = fmaxf(m1, s[t][i + 1]); m2 = fmaxf(m2, s[t][i + 2]); m3 = fmaxf(m3, s[t][i + 3]); }
;     float gm = fmaxf(fmaxf(m0, m1), fmaxf(m2, m3));
;     gm = fmaxf(gm, __shfl_xor(gm, 32));
;     if (FIRST) mx = gm;
;     else { const float mn = fmaxf(mx, gm); const float f = __builtin_amdgcn_exp2f(mx - mn); l *= f; mx = mn;
; #pragma unroll
;         for (int d = 0; d < 2; ++d)
; #pragma unroll
;             for (int i = 0; i < 16; ++i) o[d][i] *= f; }
;     float l0 = 0.f, l1 = 0.f, l2 = 0.f, l3 = 0.f;
; #pragma unroll
;     for (int t = 0; t < NT; ++t)
; #pragma unroll
;         for (int i = 0; i < 16; i += 4) {
;             const float p0 = __builtin_amdgcn_exp2f(s[t][i] - mx), p1 = __builtin_amdgcn_exp2f(s[t][i + 1] - mx), p2 = __builtin_amdgcn_exp2f(s[t][i + 2] - mx), p3 = __builtin_amdgcn_exp2f(s[t][i + 3] - mx);
;             s[t][i] = p0; s[t][i + 1] = p1; s[t][i + 2] = p2; s[t][i + 3] = p3; l0 += p0; l1 += p1; l2 += p2; l3 += p3; }
	v_mfma_f32_32x32x16_bf16 v[34:49], v[50:53], v[64:67], v[34:49]
	s_nop 11
	v_cndmask_b32_e64 v33, v34, v227, s[24:25]
	v_cndmask_b32_e64 v91, v33, v34, s[4:5]
	v_readlane_b32 s24, v250, 8
	v_max_f32_e32 v33, v20, v20
	v_max_f32_e32 v34, v16, v16
	v_readlane_b32 s25, v250, 9
	v_max_f32_e32 v33, v34, v33
	v_max3_f32 v33, v33, v24, v28
	v_cndmask_b32_e64 v113, v36, v227, s[24:25]
	v_readlane_b32 s24, v250, 10
	v_readlane_b32 s25, v250, 11
	v_max3_f32 v33, v33, v0, v4
	v_cndmask_b32_e64 v112, v227, v35, s[4:5]
	v_cndmask_b32_e64 v114, v37, v227, s[24:25]
	v_readlane_b32 s24, v250, 12
	v_max_f32_e32 v34, v21, v21
	v_max_f32_e32 v35, v17, v17
	v_max3_f32 v122, v33, v8, v12
	v_add_u32_e32 v33, v155, v148
	v_readlane_b32 s25, v250, 13
	v_max_f32_e32 v34, v35, v34
	v_max_f32_e32 v35, v23, v23
	v_max_f32_e32 v36, v19, v19
	ds_read_b128 v[50:53], v33
	ds_read_b128 v[92:95], v33 offset:4096
	v_cndmask_b32_e64 v115, v38, v227, s[24:25]
	v_readlane_b32 s24, v250, 14
	v_max_f32_e32 v35, v36, v35
	v_max3_f32 v36, v18, v22, v26
	v_max3_f32 v34, v34, v25, v29
	v_readlane_b32 s25, v250, 15
	v_max3_f32 v35, v35, v27, v31
	v_max3_f32 v36, v36, v30, v2
	v_max3_f32 v34, v34, v1, v5
	v_cndmask_b32_e64 v117, v39, v227, s[24:25]
	v_cndmask_b32_e64 v118, v40, v227, s[46:47]
	v_cndmask_b32_e64 v119, v41, v227, s[48:49]
	v_cndmask_b32_e64 v121, v42, v227, s[50:51]
	v_cndmask_b32_e64 v123, v43, v227, s[52:53]
	v_cndmask_b32_e64 v124, v44, v227, s[54:55]
	v_cndmask_b32_e64 v125, v45, v227, s[56:57]
	v_cndmask_b32_e64 v126, v46, v227, s[58:59]
	v_cndmask_b32_e64 v127, v47, v227, s[60:61]
	v_cndmask_b32_e64 v128, v48, v227, s[62:63]
	v_max3_f32 v116, v35, v3, v7
	v_max3_f32 v120, v36, v6, v10
	v_max3_f32 v130, v34, v9, v13
	v_cndmask_b32_e64 v48, 0, v32, s[66:67]
	v_mov_b32_e32 v33, v32
	v_mov_b32_e32 v34, v32
	v_mov_b32_e32 v35, v32
	v_mov_b32_e32 v36, v32
	v_mov_b32_e32 v37, v32
	v_mov_b32_e32 v38, v32
	v_mov_b32_e32 v39, v32
	v_mov_b32_e32 v40, v32
	v_mov_b32_e32 v41, v32
	v_mov_b32_e32 v42, v32
	v_mov_b32_e32 v43, v32
	v_mov_b32_e32 v44, v32
	v_mov_b32_e32 v45, v32
	v_mov_b32_e32 v46, v32
	v_mov_b32_e32 v47, v32
	v_cndmask_b32_e64 v129, v49, v227, s[64:65]
	v_mov_b32_e32 v49, v48
	s_waitcnt lgkmcnt(1)
	v_mfma_f32_32x32x16_bf16 v[32:47], v[50:53], v[76:79], v[32:47]
	v_mov_b32_e32 v50, v48
	v_mov_b32_e32 v51, v48
	v_mov_b32_e32 v52, v48
	v_mov_b32_e32 v53, v48
	v_mov_b32_e32 v54, v48
	v_mov_b32_e32 v55, v48
	v_mov_b32_e32 v56, v48
	v_mov_b32_e32 v57, v48
	v_mov_b32_e32 v58, v48
	v_mov_b32_e32 v59, v48
	v_mov_b32_e32 v60, v48
	v_mov_b32_e32 v61, v48
	v_mov_b32_e32 v62, v48
	v_mov_b32_e32 v63, v48
	ds_read_b128 v[108:111], v131
	global_load_dword v80, v[80:81], off
	s_waitcnt lgkmcnt(1)
	v_mfma_f32_32x32x16_bf16 v[48:63], v[92:95], v[76:79], v[48:63]
	v_max3_f32 v76, v116, v11, v15
	v_max3_f32 v77, v120, v14, v113
	v_max3_f32 v94, v76, v114, v119
	v_max3_f32 v95, v77, v118, v124
	ds_read_b128 v[76:79], v131 offset:4096
	v_max3_f32 v92, v122, v91, v115
	v_max3_f32 v93, v130, v112, v117
	v_max3_f32 v94, v94, v125, v129
	s_waitcnt lgkmcnt(1)
	v_mfma_f32_32x32x16_bf16 v[32:47], v[108:111], v[72:75], v[32:47]
	v_max3_f32 v92, v92, v121, v126
	v_max3_f32 v93, v93, v123, v127
	v_max3_f32 v94, v95, v128, v94
	v_add_u32_e32 v109, v155, v150
	v_max3_f32 v108, v92, v93, v94
	ds_read_b128 v[92:95], v109
	s_waitcnt lgkmcnt(1)
	v_mfma_f32_32x32x16_bf16 v[48:63], v[76:79], v[72:75], v[48:63]
	ds_bpermute_b32 v72, v157, v108
	s_waitcnt lgkmcnt(0)
	v_max_f32_e32 v76, v72, v72
	ds_read_b128 v[72:75], v109 offset:4096
	v_mfma_f32_32x32x16_bf16 v[32:47], v[92:95], v[68:71], v[32:47]
	v_max_f32_e32 v109, v108, v76
	v_add_u32_e32 v92, v155, v151
	v_sub_f32_e32 v19, v19, v109
	ds_read_b128 v[76:79], v92
	v_exp_f32_e32 v19, v19
	v_sub_f32_e32 v23, v23, v109
	v_exp_f32_e32 v23, v23
	s_waitcnt lgkmcnt(1)
	v_mfma_f32_32x32x16_bf16 v[48:63], v[72:75], v[68:71], v[48:63]
	v_add_f32_e32 v68, 0, v19
	v_sub_f32_e32 v27, v27, v109
	v_add_f32_e32 v72, v23, v68
	ds_read_b128 v[68:71], v92 offset:4096
	v_exp_f32_e32 v192, v27
	v_sub_f32_e32 v27, v31, v109
	v_exp_f32_e32 v193, v27
	s_waitcnt lgkmcnt(1)
	v_mfma_f32_32x32x16_bf16 v[32:47], v[76:79], v[64:67], v[32:47]
	v_sub_f32_e32 v3, v3, v109
	v_exp_f32_e32 v194, v3
	v_sub_f32_e32 v3, v7, v109
	v_sub_f32_e32 v20, v20, v109
	v_sub_f32_e32 v24, v24, v109
	v_exp_f32_e32 v20, v20
	v_exp_f32_e32 v81, v24
	s_waitcnt lgkmcnt(0)
	v_mfma_f32_32x32x16_bf16 v[48:63], v[68:71], v[64:67], v[48:63]
	s_nop 2
	v_cndmask_b32_e64 v27, v32, v227, s[4:5]
	v_cndmask_b32_e64 v36, v36, v227, s[90:91]
	v_cndmask_b32_e64 v31, v33, v227, s[96:97]
	v_cndmask_b32_e64 v37, v37, v227, s[88:89]
	v_max_f32_e32 v32, v36, v36
	v_max_f32_e32 v33, v27, v27
	v_cndmask_b32_e64 v35, v35, v227, s[92:93]
	v_cndmask_b32_e64 v39, v39, v227, s[6:7]
	v_max_f32_e32 v32, v33, v32
	v_max_f32_e32 v33, v37, v37
	v_max_f32_e32 v64, v31, v31
	v_max_f32_e32 v33, v64, v33
	v_max_f32_e32 v64, v39, v39
	v_max_f32_e32 v65, v35, v35
	v_cndmask_b32_e64 v34, v34, v227, s[94:95]
	v_cndmask_b32_e64 v38, v38, v227, s[42:43]
	v_cndmask_b32_e64 v42, v42, v227, s[0:1]
	v_cndmask_b32_e64 v43, v43, v227, s[2:3]
	v_cndmask_b32_e64 v47, v47, v227, s[68:69]
	v_max_f32_e32 v64, v65, v64
	v_cndmask_b32_e64 v40, v40, v227, s[40:41]
	v_cndmask_b32_e64 v41, v41, v227, s[38:39]
	v_cndmask_b32_e64 v44, v44, v227, s[28:29]
	v_cndmask_b32_e64 v45, v45, v227, s[76:77]
	v_cndmask_b32_e64 v46, v46, v227, s[70:71]
	v_max3_f32 v65, v34, v38, v42
	v_max3_f32 v64, v64, v43, v47
	v_max3_f32 v32, v32, v40, v44
	v_max3_f32 v33, v33, v41, v45
	v_max3_f32 v65, v65, v46, v50
	v_max3_f32 v64, v64, v51, v55
	v_max3_f32 v32, v32, v48, v52
	v_max3_f32 v33, v33, v49, v53
	v_max3_f32 v65, v65, v54, v58
	v_max3_f32 v64, v64, v59, v63
	v_max3_f32 v32, v32, v56, v60
	v_max3_f32 v33, v33, v57, v61
	v_max3_f32 v64, v65, v62, v64
	v_max3_f32 v32, v32, v33, v64
	ds_bpermute_b32 v33, v157, v32
	v_exp_f32_e32 v66, v3
	v_sub_f32_e32 v24, v25, v109
	v_sub_f32_e32 v0, v0, v109
	v_exp_f32_e32 v198, v0
	s_waitcnt lgkmcnt(0)
; template <int T0, int NT, bool FIRST>
; __device__ __forceinline__ void attn_group(LAS const unsigned char* Kl, LAS const unsigned char* Vl, const bf16x8 (&qf)[4], f32x16 (&o)[2], float& mx, float& l, int nb, int w, int lane) {
;     ...
;     float m0 = s[0][0], m1 = s[0][1], m2 = s[0][2], m3 = s[0][3];
; #pragma unroll
;     for (int t = 0; t < NT; ++t)
; #pragma unroll
;         for (int i = 0; i < 16; i += 4) { m0 = fmaxf(m0, s[t][i]); m1 = fmaxf(m1, s[t][i + 1]); m2 = fmaxf(m2, s[t][i + 2]); m3 = fmaxf(m3, s[t][i + 3]); }
;     float gm = fmaxf(fmaxf(m0, m1), fmaxf(m2, m3));
;     gm = fmaxf(gm, __shfl_xor(gm, 32));
;     if (FIRST) mx = gm;
;     else { const float mn = fmaxf(mx, gm); const float f = __builtin_amdgcn_exp2f(mx - mn); l *= f; mx = mn;
; #pragma unroll
;         for (int d = 0; d < 2; ++d)
; #pragma unroll
;             for (int i = 0; i < 16; ++i) o[d][i] *= f; }
;     float l0 = 0.f, l1 = 0.f, l2 = 0.f, l3 = 0.f;
; #pragma unroll
;     for (int t = 0; t < NT; ++t)
; #pragma unroll
;         for (int i = 0; i < 16; i += 4) {
;             const float p0 = __builtin_amdgcn_exp2f(s[t][i] - mx), p1 = __builtin_amdgcn_exp2f(s[t][i + 1] - mx), p2 = __builtin_amdgcn_exp2f(s[t][i + 2] - mx), p3 = __builtin_amdgcn_exp2f(s[t][i + 3] - mx);
;             s[t][i] = p0; s[t][i + 1] = p1; s[t][i + 2] = p2; s[t][i + 3] = p3; l0 += p0; l1 += p1; l2 += p2; l3 += p3; }
;     l += (l0 + l1) + (l2 + l3);
; template <bool FINAL>
; __device__ __forceinline__ void attn_compute(LAS unsigned char* lds, const bf16_t* proj, const AttnItem& t, const AttnItem& nxt, bool more, bf16x8 (&qf)[4], bf16_t* o23, float* lse23, bf16_t* ycat, int lane, int wid) {
;     ...
;     l += __shfl_xor(l, 32);
	v_max3_f32 v7, v109, v32, v33
	v_sub_f32_e32 v3, v27, v7
	v_exp_f32_e32 v67, v3
	v_add_f32_e32 v3, v192, v72
	v_add_f32_e32 v3, v193, v3
	v_add_f32_e32 v168, v194, v3
	v_and_or_b32 v3, v90, s10, v145
	v_pk_add_f32 v[32:33], v[66:67], v[168:169]
	v_lshlrev_b32_e32 v168, 7, v3
	v_sub_f32_e32 v3, v16, v109
	v_exp_f32_e32 v16, v3
	global_load_dword v27, v[82:83], off
	v_sub_f32_e32 v3, v17, v109
	v_exp_f32_e32 v82, v24
	v_sub_f32_e32 v24, v26, v109
	v_sub_f32_e32 v26, v28, v109
	v_exp_f32_e32 v17, v3
	v_sub_f32_e32 v3, v18, v109
	v_exp_f32_e32 v195, v26
	v_exp_f32_e32 v18, v3
	v_add_f32_e32 v3, 0, v16
	v_add_f32_e32 v3, v20, v3
	v_add_f32_e32 v3, v81, v3
	v_sub_f32_e32 v0, v1, v109
	v_add_f32_e32 v3, v195, v3
	v_exp_f32_e32 v199, v0
	v_sub_f32_e32 v0, v2, v109
	v_exp_f32_e32 v200, v0
	v_add_f32_e32 v0, v198, v3
	v_sub_f32_e32 v3, v5, v109
	v_exp_f32_e32 v201, v3
	v_sub_f32_e32 v3, v6, v109
	v_exp_f32_e32 v202, v3
	v_sub_f32_e32 v3, v4, v109
	v_exp_f32_e32 v116, v3
	v_sub_f32_e32 v3, v8, v109
	v_exp_f32_e32 v120, v3
	v_sub_f32_e32 v3, v9, v109
	v_exp_f32_e32 v203, v3
	v_sub_f32_e32 v3, v10, v109
	v_exp_f32_e32 v204, v3
	v_sub_f32_e32 v3, v11, v109
	v_exp_f32_e32 v122, v3
	v_sub_f32_e32 v3, v12, v109
	v_exp_f32_e32 v92, v3
	v_sub_f32_e32 v3, v13, v109
	v_exp_f32_e32 v205, v3
	v_sub_f32_e32 v3, v14, v109
	v_exp_f32_e32 v206, v3
	v_sub_f32_e32 v3, v15, v109
	v_exp_f32_e32 v94, v3
	v_sub_f32_e32 v3, v91, v109
	v_exp_f32_e32 v108, v3
	v_sub_f32_e32 v3, v112, v109
	v_exp_f32_e32 v207, v3
	v_sub_f32_e32 v3, v113, v109
	v_exp_f32_e32 v208, v3
	v_sub_f32_e32 v3, v114, v109
	v_sub_f32_e32 v22, v22, v109
	v_exp_f32_e32 v112, v3
	v_sub_f32_e32 v3, v115, v109
	v_exp_f32_e32 v22, v22
	v_sub_f32_e32 v26, v29, v109
	v_exp_f32_e32 v76, v3
	v_sub_f32_e32 v3, v117, v109
	v_exp_f32_e32 v83, v24
	v_exp_f32_e32 v196, v26
	v_sub_f32_e32 v26, v30, v109
	v_exp_f32_e32 v209, v3
	v_sub_f32_e32 v3, v118, v109
	v_sub_f32_e32 v21, v21, v109
	v_exp_f32_e32 v197, v26
	v_exp_f32_e32 v210, v3
	v_sub_f32_e32 v3, v119, v109
	v_add_f32_e32 v69, 0, v18
	v_exp_f32_e32 v21, v21
	v_exp_f32_e32 v78, v3
	v_sub_f32_e32 v3, v121, v109
	v_add_f32_e32 v24, v22, v69
	v_exp_f32_e32 v90, v3
	v_sub_f32_e32 v3, v123, v109
	v_add_f32_e32 v24, v83, v24
	v_exp_f32_e32 v211, v3
	v_sub_f32_e32 v3, v124, v109
	v_add_f32_e32 v68, 0, v17
	v_add_f32_e32 v1, v197, v24
	v_exp_f32_e32 v212, v3
	v_sub_f32_e32 v3, v125, v109
	v_add_f32_e32 v68, v21, v68
	v_add_f32_e32 v1, v200, v1
	v_exp_f32_e32 v110, v3
	v_sub_f32_e32 v3, v126, v109
	v_add_f32_e32 v25, v82, v68
	v_add_f32_e32 v1, v202, v1
	v_exp_f32_e32 v68, v3
	v_sub_f32_e32 v3, v127, v109
	v_add_f32_e32 v1, v204, v1
	v_exp_f32_e32 v213, v3
	v_sub_f32_e32 v3, v128, v109
	v_add_f32_e32 v1, v206, v1
	v_exp_f32_e32 v214, v3
	v_add_f32_e32 v1, v208, v1
	v_add_f32_e32 v1, v210, v1
	v_add_f32_e32 v1, v212, v1
	v_add_f32_e32 v74, v214, v1
	v_sub_f32_e32 v1, v109, v7
	v_exp_f32_e32 v136, v1
	v_sub_f32_e32 v1, v45, v7
	v_sub_f32_e32 v3, v129, v109
	v_exp_f32_e32 v109, v1
	v_sub_f32_e32 v1, v46, v7
	v_exp_f32_e32 v130, v1
	v_sub_f32_e32 v1, v47, v7
	v_exp_f32_e32 v131, v1
	v_sub_f32_e32 v1, v48, v7
	v_exp_f32_e32 v79, v1
	v_sub_f32_e32 v1, v49, v7
	v_exp_f32_e32 v77, v1
	v_sub_f32_e32 v1, v50, v7
	v_add_f32_e32 v25, v196, v25
	v_exp_f32_e32 v124, v1
	v_sub_f32_e32 v1, v51, v7
	v_add_f32_e32 v2, v199, v25
	v_exp_f32_e32 v125, v1
	v_sub_f32_e32 v1, v52, v7
	v_add_f32_e32 v2, v201, v2
	v_exp_f32_e32 v111, v1
	v_sub_f32_e32 v1, v53, v7
	v_add_f32_e32 v2, v203, v2
	v_sub_f32_e32 v4, v31, v7
	v_exp_f32_e32 v91, v1
	v_sub_f32_e32 v1, v54, v7
	v_add_f32_e32 v2, v205, v2
	v_exp_f32_e32 v117, v4
	v_sub_f32_e32 v4, v34, v7
	v_exp_f32_e32 v126, v1
	v_sub_f32_e32 v1, v55, v7
	v_add_f32_e32 v2, v207, v2
	v_exp_f32_e32 v132, v4
	v_sub_f32_e32 v4, v35, v7
	v_exp_f32_e32 v127, v1
	v_sub_f32_e32 v1, v56, v7
	v_add_f32_e32 v2, v209, v2
	v_exp_f32_e32 v133, v4
	v_sub_f32_e32 v4, v36, v7
	v_exp_f32_e32 v71, v1
	v_sub_f32_e32 v1, v57, v7
	v_add_f32_e32 v2, v211, v2
	v_exp_f32_e32 v123, v4
	v_sub_f32_e32 v4, v37, v7
	v_exp_f32_e32 v69, v1
	v_sub_f32_e32 v1, v58, v7
	v_exp_f32_e32 v121, v4
	v_sub_f32_e32 v4, v38, v7
	v_add_f32_e32 v72, v213, v2
	v_sub_f32_e32 v2, v41, v7
	v_exp_f32_e32 v114, v1
	v_sub_f32_e32 v1, v59, v7
	v_exp_f32_e32 v134, v4
	v_sub_f32_e32 v4, v39, v7
	v_exp_f32_e32 v93, v2
	v_sub_f32_e32 v2, v42, v7
	v_exp_f32_e32 v115, v1
	v_sub_f32_e32 v1, v60, v7
	v_exp_f32_e32 v135, v4
	v_exp_f32_e32 v128, v2
	v_sub_f32_e32 v2, v43, v7
	v_exp_f32_e32 v75, v1
	v_sub_f32_e32 v1, v61, v7
	v_exp_f32_e32 v70, v3
	v_sub_f32_e32 v3, v40, v7
	v_exp_f32_e32 v129, v2
	v_exp_f32_e32 v73, v1
	v_sub_f32_e32 v1, v62, v7
	v_exp_f32_e32 v95, v3
	v_sub_f32_e32 v2, v44, v7
	v_exp_f32_e32 v118, v1
	v_sub_f32_e32 v1, v63, v7
	v_exp_f32_e32 v113, v2
	v_exp_f32_e32 v119, v1
	v_pk_add_f32 v[2:3], v[132:133], 0 op_sel_hi:[1,0]
	v_mov_b32_e32 v1, v169
	v_pk_add_f32 v[2:3], v[134:135], v[2:3]
	v_pk_add_f32 v[0:1], v[116:117], v[0:1]
	v_pk_add_f32 v[2:3], v[128:129], v[2:3]
	v_pk_add_f32 v[4:5], v[122:123], v[32:33]
	v_pk_add_f32 v[0:1], v[120:121], v[0:1]
	v_pk_add_f32 v[2:3], v[130:131], v[2:3]
	v_pk_add_f32 v[4:5], v[94:95], v[4:5]
	v_pk_add_f32 v[0:1], v[92:93], v[0:1]
	v_pk_add_f32 v[2:3], v[124:125], v[2:3]
	v_pk_add_f32 v[4:5], v[112:113], v[4:5]
	v_pk_add_f32 v[0:1], v[108:109], v[0:1]
	v_pk_add_f32 v[2:3], v[126:127], v[2:3]
	v_pk_add_f32 v[4:5], v[78:79], v[4:5]
	v_pk_add_f32 v[0:1], v[76:77], v[0:1]
	v_pk_add_f32 v[2:3], v[114:115], v[2:3]
	v_pk_add_f32 v[4:5], v[110:111], v[4:5]
	v_pk_add_f32 v[0:1], v[90:91], v[0:1]
	v_pk_add_f32 v[2:3], v[118:119], v[2:3]
	v_pk_add_f32 v[4:5], v[70:71], v[4:5]
	v_pk_add_f32 v[0:1], v[68:69], v[0:1]
	v_pk_add_f32 v[2:3], v[2:3], v[2:3] op_sel_hi:[0,1]
	v_pk_add_f32 v[4:5], v[74:75], v[4:5]
	v_pk_add_f32 v[0:1], v[72:73], v[0:1]
	v_mov_b32_e32 v2, v169
	v_pk_add_f32 v[0:1], v[4:5], v[0:1]
	v_lshl_add_u64 v[64:65], vcc, 0, v[168:169]
	v_pk_add_f32 v[0:1], v[0:1], v[2:3]
	v_add_u32_e32 v72, v152, v153
	v_fmac_f32_e32 v1, v0, v136
	ds_bpermute_b32 v0, v157, v1
	v_add_u32_e32 v74, v152, v154
	v_and_b32_e32 v52, 0xfffff800, v86
	v_bfe_u32 v54, v86, 4, 7
	v_cvt_pk_bf16_f32 v60, v81, v82
	s_waitcnt lgkmcnt(0)
; #define LAS __attribute__((address_space(3)))
; __device__ __forceinline__ s16x4 vtr(LAS const unsigned char* p) { return __builtin_bit_cast(s16x4, __builtin_amdgcn_ds_read_tr16_b64_v4i16((LAS v4i16_t*)p)); }
; template <int T0, int NT, bool FIRST>
; __device__ __forceinline__ void attn_group(LAS const unsigned char* Kl, LAS const unsigned char* Vl, const bf16x8 (&qf)[4], f32x16 (&o)[2], float& mx, float& l, int nb, int w, int lane) {
;     ...
;     const int i16 = lane & 15, q4 = i16 >> 2, p4 = i16 & 3, blk = (lane >> 4) & 1;
;     LAS const unsigned char* vb = Vl + (32 * (w + T0) + 4 * hi + q4) * 128 + 32 * blk + 8 * p4;
;     const int vsw = ((q4 >> 1) & 1) * 64;
; #pragma unroll
;     for (int t = 0; t < NT; ++t)
; #pragma unroll
;         for (int s2 = 0; s2 < 2; ++s2) {
;             u32x4 pw; pw.x = cvt_pk_bf16(s[t][8 * s2 + 0], s[t][8 * s2 + 1]); pw.y = cvt_pk_bf16(s[t][8 * s2 + 2], s[t][8 * s2 + 3]);
;             pw.z = cvt_pk_bf16(s[t][8 * s2 + 4], s[t][8 * s2 + 5]); pw.w = cvt_pk_bf16(s[t][8 * s2 + 6], s[t][8 * s2 + 7]);
;             const bf16x8 pf = __builtin_bit_cast(bf16x8, pw);
; #pragma unroll
;             for (int d = 0; d < 2; ++d) {
;                 LAS const unsigned char* vp = vb + (t * 32 + s2 * 16) * 128 + ((d * 64) ^ vsw);
;                 const s16x4 lo = vtr(vp), hi4 = vtr(vp + 8 * 128);
;                 const bf16x8 vf = (bf16x8){lo[0], lo[1], lo[2], lo[3], hi4[0], hi4[1], hi4[2], hi4[3]};
;                 o[d] = __builtin_amdgcn_mfma_f32_32x32x16_bf16(vf, pf, o[d], 0, 0, 0);
;             }
;         }
; template <bool FINAL>
; __device__ __forceinline__ void attn_compute(LAS unsigned char* lds, const bf16_t* proj, const AttnItem& t, const AttnItem& nxt, bool more, bf16x8 (&qf)[4], bf16_t* o23, float* lse23, bf16_t* ycat, int lane, int wid) {
;     ...
;     } else {
;         const float mm = fmaxf(lse, fmaxf(l2, l3));
;         const float e1 = __builtin_amdgcn_exp2f(lse - mm), e2 = __builtin_amdgcn_exp2f(l2 - mm), e3 = __builtin_amdgcn_exp2f(l3 - mm);
;         const float inv = 1.0f / (e1 + e2 + e3);
;         const float c1 = e1 * inv / l, c2 = e2 * inv, c3 = e3 * inv;
	v_add_f32_e32 v168, v1, v0
	v_log_f32_e32 v0, v168
	v_cvt_pk_bf16_f32 v61, v83, v192
	v_cvt_pk_bf16_f32 v62, v195, v196
	v_cvt_pk_bf16_f32 v63, v197, v193
	v_add_f32_e32 v0, v7, v0
	s_waitcnt vmcnt(0)
	v_max3_f32 v1, v0, v27, v80
	v_sub_f32_e32 v0, v0, v1
	v_sub_f32_e32 v2, v27, v1
	v_exp_f32_e32 v0, v0
	v_exp_f32_e32 v189, v2
	v_sub_f32_e32 v1, v80, v1
	v_exp_f32_e32 v190, v1
	v_cvt_pk_bf16_f32 v7, v22, v23
	v_add_f32_e32 v1, v0, v189
	v_cvt_pk_bf16_f32 v196, v120, v203
	v_add_f32_e32 v1, v190, v1
	v_div_scale_f32 v2, s[24:25], v1, v1, 1.0
	v_rcp_f32_e32 v3, v2
	v_cvt_pk_bf16_f32 v197, v204, v122
	v_lshl_add_u64 v[64:65], v[96:97], 1, v[64:65]
	v_fma_f32 v4, -v2, v3, 1.0
	v_fmac_f32_e32 v3, v4, v3
	v_div_scale_f32 v4, vcc, 1.0, v1, 1.0
	v_mul_f32_e32 v5, v4, v3
	v_fma_f32 v6, -v2, v5, v4
	v_fmac_f32_e32 v5, v6, v3
	v_fma_f32 v2, -v2, v5, v4
	v_div_fmas_f32 v2, v2, v3, v5
	v_div_fixup_f32 v191, v2, v1, 1.0
	v_mul_f32_e32 v215, v0, v191
	v_div_scale_f32 v0, s[24:25], v168, v168, v215
	v_rcp_f32_e32 v1, v0
	v_cvt_pk_bf16_f32 v5, v18, v19
	v_cvt_pk_bf16_f32 v6, v20, v21
	s_lshl_b64 s[24:25], s[98:99], 24
	v_fma_f32 v2, -v0, v1, 1.0
	v_fmac_f32_e32 v1, v2, v1
	v_div_scale_f32 v2, vcc, v215, v168, v215
	v_mul_f32_e32 v3, v2, v1
	v_fma_f32 v4, -v0, v3, v2
	v_fmac_f32_e32 v3, v4, v1
	v_fma_f32 v0, -v0, v3, v2
	v_div_fmas_f32 v216, v0, v1, v3
	v_lshlrev_b32_e32 v1, 7, v187
	v_and_b32_e32 v0, 0xfffff800, v187
	v_and_b32_e32 v1, 0x780, v1
	v_bfe_u32 v2, v187, 4, 7
	v_or3_b32 v0, v1, v0, v2
	v_ashrrev_i32_e32 v1, 31, v0
	v_lshlrev_b64 v[0:1], 8, v[0:1]
	v_lshl_add_u64 v[0:1], v[88:89], 0, v[0:1]
	global_load_dwordx4 v[32:35], v[0:1], off
	global_load_dwordx4 v[36:39], v[0:1], off offset:128
	v_lshlrev_b32_e32 v1, 7, v87
	v_and_b32_e32 v0, 0xfffff800, v87
	v_and_b32_e32 v1, 0x780, v1
	v_bfe_u32 v2, v87, 4, 7
	v_or3_b32 v0, v1, v0, v2
	v_ashrrev_i32_e32 v1, 31, v0
	v_lshlrev_b64 v[0:1], 8, v[0:1]
	v_lshl_add_u64 v[12:13], v[88:89], 0, v[0:1]
	ds_read_b64_tr_b16 v[0:1], v72 offset:49152
	ds_read_b64_tr_b16 v[2:3], v72 offset:50176
	global_load_dwordx4 v[40:43], v[12:13], off
	v_cvt_pk_bf16_f32 v4, v16, v17
	ds_read_b64_tr_b16 v[8:9], v74 offset:49152
	ds_read_b64_tr_b16 v[10:11], v74 offset:50176
	s_waitcnt lgkmcnt(2)
	v_mfma_f32_32x32x16_bf16 v[16:31], v[0:3], v[4:7], 0
	global_load_dwordx4 v[44:47], v[12:13], off offset:128
	v_lshlrev_b32_e32 v0, 7, v86
	ds_read_b64_tr_b16 v[48:49], v72 offset:51200
	ds_read_b64_tr_b16 v[50:51], v72 offset:52224
	v_and_b32_e32 v53, 0x780, v0
	v_or3_b32 v52, v53, v52, v54
	ds_read_b64_tr_b16 v[56:57], v74 offset:51200
	ds_read_b64_tr_b16 v[58:59], v74 offset:52224
	v_ashrrev_i32_e32 v53, 31, v52
	s_waitcnt lgkmcnt(4)
	v_mfma_f32_32x32x16_bf16 v[0:15], v[8:11], v[4:7], 0
	v_and_b32_e32 v86, 0xfffff800, v85
	s_add_u32 s24, s26, s24
	s_addc_u32 s25, s27, s25
	s_lshl_b32 s12, s12, 7
	s_cmp_lg_u32 s15, s17
	s_mov_b32 s98, s20
	s_waitcnt lgkmcnt(2)
	v_mfma_f32_32x32x16_bf16 v[16:31], v[48:51], v[60:63], v[16:31]
	v_lshlrev_b64 v[48:49], 8, v[52:53]
	v_lshl_add_u64 v[52:53], v[88:89], 0, v[48:49]
	global_load_dwordx4 v[48:51], v[52:53], off
	s_nop 0
	global_load_dwordx4 v[52:55], v[52:53], off offset:128
	ds_read_b64_tr_b16 v[80:81], v72 offset:53248
	ds_read_b64_tr_b16 v[82:83], v72 offset:54272
	s_waitcnt lgkmcnt(2)
	v_mfma_f32_32x32x16_bf16 v[0:15], v[56:59], v[60:63], v[0:15]
	v_cvt_pk_bf16_f32 v56, v198, v199
	v_cvt_pk_bf16_f32 v57, v200, v194
	ds_read_b64_tr_b16 v[60:61], v74 offset:53248
	ds_read_b64_tr_b16 v[62:63], v74 offset:54272
	v_cvt_pk_bf16_f32 v58, v116, v201
	v_cvt_pk_bf16_f32 v59, v202, v66
	v_lshlrev_b32_e32 v66, 7, v85
	v_and_b32_e32 v66, 0x780, v66
	s_waitcnt lgkmcnt(2)
	v_mfma_f32_32x32x16_bf16 v[16:31], v[80:83], v[56:59], v[16:31]
	v_bfe_u32 v80, v85, 4, 7
	v_or3_b32 v86, v66, v86, v80
	ds_read_b64_tr_b16 v[80:81], v72 offset:55296
	ds_read_b64_tr_b16 v[82:83], v72 offset:56320
	ds_read_b64_tr_b16 v[192:193], v74 offset:55296
	ds_read_b64_tr_b16 v[194:195], v74 offset:56320
	v_cvt_pk_bf16_f32 v198, v92, v205
	v_cvt_pk_bf16_f32 v199, v206, v94
	v_ashrrev_i32_e32 v87, 31, v86
	s_waitcnt lgkmcnt(4)
	v_mfma_f32_32x32x16_bf16 v[0:15], v[60:63], v[56:59], v[0:15]
	v_lshlrev_b64 v[56:57], 8, v[86:87]
	v_lshl_add_u64 v[60:61], v[88:89], 0, v[56:57]
	global_load_dwordx4 v[56:59], v[60:61], off
	s_nop 0
	global_load_dwordx4 v[60:63], v[60:61], off offset:128
	v_lshlrev_b32_e32 v85, 7, v84
	v_and_b32_e32 v66, 0xfffff800, v84
	v_and_b32_e32 v85, 0x780, v85
	v_cvt_pk_bf16_f32 v92, v95, v93
	s_waitcnt lgkmcnt(2)
	v_mfma_f32_32x32x16_bf16 v[16:31], v[80:83], v[196:199], v[16:31]
	ds_read_b64_tr_b16 v[80:81], v72 offset:57344
	ds_read_b64_tr_b16 v[82:83], v72 offset:58368
	v_cvt_pk_bf16_f32 v93, v128, v129
	v_cvt_pk_bf16_f32 v94, v113, v109
	v_cvt_pk_bf16_f32 v95, v130, v131
	s_waitcnt lgkmcnt(2)
	v_mfma_f32_32x32x16_bf16 v[0:15], v[192:195], v[196:199], v[0:15]
	ds_read_b64_tr_b16 v[192:193], v74 offset:57344
	ds_read_b64_tr_b16 v[194:195], v74 offset:58368
	v_cvt_pk_bf16_f32 v196, v108, v207
	v_cvt_pk_bf16_f32 v197, v208, v112
	v_cvt_pk_bf16_f32 v198, v76, v209
	v_cvt_pk_bf16_f32 v199, v210, v78
	v_bfe_u32 v76, v84, 4, 7
	v_cvt_pk_bf16_f32 v78, v111, v91
	s_waitcnt lgkmcnt(2)
	v_mfma_f32_32x32x16_bf16 v[16:31], v[80:83], v[196:199], v[16:31]
	v_or3_b32 v80, v85, v66, v76
	ds_read_b64_tr_b16 v[84:85], v72 offset:59392
	ds_read_b64_tr_b16 v[86:87], v72 offset:60416
	v_ashrrev_i32_e32 v81, 31, v80
	v_lshlrev_b64 v[80:81], 8, v[80:81]
	v_lshl_add_u64 v[200:201], v[88:89], 0, v[80:81]
	global_load_dwordx4 v[80:83], v[200:201], off
	v_add_u32_e32 v72, v156, v154
	s_waitcnt lgkmcnt(2)
; #define LAS __attribute__((address_space(3)))
; template <int T0, int NT, bool FIRST>
; __device__ __forceinline__ void attn_group(LAS const unsigned char* Kl, LAS const unsigned char* Vl, const bf16x8 (&qf)[4], f32x16 (&o)[2], float& mx, float& l, int nb, int w, int lane) {
;     ...
;     const int i16 = lane & 15, q4 = i16 >> 2, p4 = i16 & 3, blk = (lane >> 4) & 1;
;     LAS const unsigned char* vb = Vl + (32 * (w + T0) + 4 * hi + q4) * 128 + 32 * blk + 8 * p4;
;     const int vsw = ((q4 >> 1) & 1) * 64;
; #pragma unroll
;     for (int t = 0; t < NT; ++t)
; #pragma unroll
;         for (int s2 = 0; s2 < 2; ++s2) {
;             u32x4 pw; pw.x = cvt_pk_bf16(s[t][8 * s2 + 0], s[t][8 * s2 + 1]); pw.y = cvt_pk_bf16(s[t][8 * s2 + 2], s[t][8 * s2 + 3]);
;             pw.z = cvt_pk_bf16(s[t][8 * s2 + 4], s[t][8 * s2 + 5]); pw.w = cvt_pk_bf16(s[t][8 * s2 + 6], s[t][8 * s2 + 7]);
;             const bf16x8 pf = __builtin_bit_cast(bf16x8, pw);
; #pragma unroll
;             for (int d = 0; d < 2; ++d) {
;                 LAS const unsigned char* vp = vb + (t * 32 + s2 * 16) * 128 + ((d * 64) ^ vsw);
;                 const s16x4 lo = vtr(vp), hi4 = vtr(vp + 8 * 128);
;                 const bf16x8 vf = (bf16x8){lo[0], lo[1], lo[2], lo[3], hi4[0], hi4[1], hi4[2], hi4[3]};
;                 o[d] = __builtin_amdgcn_mfma_f32_32x32x16_bf16(vf, pf, o[d], 0, 0, 0);
;             }
;         }
; }
; template <bool FINAL>
; __device__ __forceinline__ void attn_compute(LAS unsigned char* lds, const bf16_t* proj, const AttnItem& t, const AttnItem& nxt, bool more, bf16x8 (&qf)[4], bf16_t* o23, float* lse23, bf16_t* ycat, int lane, int wid) {
;     const int w = wid & 3, r32 = lane & 31, hi = lane >> 5;
;     LAS unsigned char* Kl = lds + (wid >> 2) * 16384; LAS unsigned char* Vl = Kl + 49152;
;     const int nb = t.nb;
;     const int tok = (nb * 128 + 32 * w + r32) * t.dil + t.r;
;     const size_t qrow = (size_t)t.b * SEQ + tok, hrow = (size_t)(t.b * NH + t.h) * SEQ + tpos(tok);
;     float l2 = 0.f, l3 = 0.f; u32x2 a2[8], a3[8];
;     if (FINAL) { l2 = lse23[hrow]; l3 = lse23[(size_t)M * NH + hrow];
;         const bf16_t* o2 = o23 + hrow * HD + 4 * hi; const bf16_t* o3 = o2 + (size_t)M * AW;
; #pragma unroll
;         for (int i = 0; i < 8; ++i) { a2[i] = *(const u32x2*)(o2 + 32 * (i >> 2) + 8 * (i & 3)); a3[i] = *(const u32x2*)(o3 + 32 * (i >> 2) + 8 * (i & 3)); } }
	v_mfma_f32_32x32x16_bf16 v[0:15], v[192:195], v[196:199], v[0:15]
	ds_read_b64_tr_b16 v[192:193], v74 offset:59392
	ds_read_b64_tr_b16 v[194:195], v74 offset:60416
	v_cvt_pk_bf16_f32 v196, v90, v211
	v_cvt_pk_bf16_f32 v197, v212, v110
	v_cvt_pk_bf16_f32 v198, v68, v213
	v_cvt_pk_bf16_f32 v199, v214, v70
	v_add_u32_e32 v70, v156, v153
	v_lshlrev_b32_e32 v68, 7, v186
	s_waitcnt lgkmcnt(2)
	v_mfma_f32_32x32x16_bf16 v[16:31], v[84:87], v[196:199], v[16:31]
	global_load_dwordx4 v[84:87], v[200:201], off offset:128
	s_nop 0
	global_load_dwordx2 v[200:201], v[106:107], off
	global_load_dwordx2 v[202:203], v[106:107], off offset:16
	global_load_dwordx2 v[204:205], v[104:105], off
	v_and_b32_e32 v66, 0xfffff800, v186
	v_and_b32_e32 v68, 0x780, v68
	v_cvt_pk_bf16_f32 v76, v79, v77
	v_cvt_pk_bf16_f32 v77, v124, v125
	v_cvt_pk_bf16_f32 v79, v126, v127
	s_waitcnt lgkmcnt(0)
	v_mfma_f32_32x32x16_bf16 v[0:15], v[192:195], v[196:199], v[0:15]
	ds_read_b64_tr_b16 v[192:193], v70 offset:49152
	ds_read_b64_tr_b16 v[194:195], v70 offset:50176
	v_mul_f32_e64 v30, v30, v136
	v_mul_f32_e64 v31, v31, v136
	v_mul_f32_e64 v28, v28, v136
	v_mul_f32_e64 v29, v29, v136
	v_pk_mul_f32 v[26:27], v[26:27], v[136:137] op_sel_hi:[1,0]
	v_pk_mul_f32 v[24:25], v[24:25], v[136:137] op_sel_hi:[1,0]
	v_pk_mul_f32 v[22:23], v[22:23], v[136:137] op_sel_hi:[1,0]
	v_pk_mul_f32 v[20:21], v[20:21], v[136:137] op_sel_hi:[1,0]
	v_pk_mul_f32 v[18:19], v[18:19], v[136:137] op_sel_hi:[1,0]
	v_pk_mul_f32 v[16:17], v[16:17], v[136:137] op_sel_hi:[1,0]
	v_cvt_pk_bf16_f32 v196, v67, v117
	v_cvt_pk_bf16_f32 v197, v132, v133
	v_cvt_pk_bf16_f32 v198, v123, v121
	v_cvt_pk_bf16_f32 v199, v134, v135
	ds_read_b64_tr_b16 v[120:121], v72 offset:49152
	ds_read_b64_tr_b16 v[122:123], v72 offset:50176
	s_waitcnt lgkmcnt(2)
	v_mfma_f32_32x32x16_bf16 v[16:31], v[192:195], v[196:199], v[16:31]
	ds_read_b64_tr_b16 v[132:133], v70 offset:51200
	ds_read_b64_tr_b16 v[134:135], v70 offset:52224
	global_load_dwordx2 v[116:117], v[104:105], off offset:16
	v_mul_f32_e64 v14, v14, v136
	v_mul_f32_e64 v15, v15, v136
	v_pk_mul_f32 v[12:13], v[12:13], v[136:137] op_sel_hi:[1,0]
	v_pk_mul_f32 v[10:11], v[10:11], v[136:137] op_sel_hi:[1,0]
	v_pk_mul_f32 v[8:9], v[8:9], v[136:137] op_sel_hi:[1,0]
	v_pk_mul_f32 v[6:7], v[6:7], v[136:137] op_sel_hi:[1,0]
	v_pk_mul_f32 v[4:5], v[4:5], v[136:137] op_sel_hi:[1,0]
	v_pk_mul_f32 v[2:3], v[2:3], v[136:137] op_sel_hi:[1,0]
	v_pk_mul_f32 v[0:1], v[0:1], v[136:137] op_sel_hi:[1,0]
	s_waitcnt lgkmcnt(0)
	v_mfma_f32_32x32x16_bf16 v[16:31], v[132:135], v[92:95], v[16:31]
	v_bfe_u32 v67, v186, 4, 7
	v_or3_b32 v66, v68, v66, v67
	v_ashrrev_i32_e32 v67, 31, v66
	v_lshlrev_b64 v[66:67], 8, v[66:67]
	v_lshl_add_u64 v[66:67], v[88:89], 0, v[66:67]
	v_cvt_pk_bf16_f32 v68, v75, v73
	v_mul_f32_e32 v112, v189, v191
	v_mfma_f32_32x32x16_bf16 v[0:15], v[120:123], v[196:199], v[0:15]
	ds_read_b64_tr_b16 v[120:121], v72 offset:51200
	ds_read_b64_tr_b16 v[122:123], v72 offset:52224
	global_load_dwordx2 v[132:133], v[106:107], off offset:32
	ds_read_b64_tr_b16 v[128:129], v70 offset:53248
	ds_read_b64_tr_b16 v[130:131], v70 offset:54272
	global_load_dwordx2 v[134:135], v[104:105], off offset:32
	ds_read_b64_tr_b16 v[108:109], v72 offset:53248
	ds_read_b64_tr_b16 v[110:111], v72 offset:54272
	s_waitcnt vmcnt(5)
	v_and_b32_e32 v189, 0xffff0000, v200
	s_waitcnt lgkmcnt(4)
	v_mfma_f32_32x32x16_bf16 v[0:15], v[120:123], v[92:95], v[0:15]
	global_load_dwordx4 v[88:91], v[66:67], off
	global_load_dwordx4 v[92:95], v[66:67], off offset:128
	global_load_dwordx2 v[124:125], v[106:107], off offset:48
	global_load_dwordx2 v[126:127], v[104:105], off offset:48
	ds_read_b64_tr_b16 v[120:121], v70 offset:55296
	ds_read_b64_tr_b16 v[122:123], v70 offset:56320
	v_cvt_pk_bf16_f32 v66, v71, v69
	v_cvt_pk_bf16_f32 v67, v114, v115
	v_cvt_pk_bf16_f32 v69, v118, v119
	v_div_fixup_f32 v114, v216, v168, v215
	v_lshlrev_b32_e32 v168, 11, v188
	s_waitcnt lgkmcnt(4)
	v_mfma_f32_32x32x16_bf16 v[16:31], v[128:131], v[76:79], v[16:31]
	global_load_dwordx2 v[128:129], v[106:107], off offset:64
	v_lshlrev_b32_e32 v188, 16, v200
	s_waitcnt lgkmcnt(2)
	v_mfma_f32_32x32x16_bf16 v[0:15], v[108:111], v[76:79], v[0:15]
	ds_read_b64_tr_b16 v[76:77], v72 offset:55296
	ds_read_b64_tr_b16 v[78:79], v72 offset:56320
	v_mul_f32_e32 v110, v190, v191
	v_lshl_add_u64 v[108:109], s[24:25], 0, v[168:169]
	v_lshl_add_u64 v[108:109], v[108:109], 0, s[12:13]
	v_lshl_add_u64 v[108:109], v[102:103], 1, v[108:109]
	s_mov_b32 s12, s21
	s_waitcnt lgkmcnt(2)
	v_mfma_f32_32x32x16_bf16 v[16:31], v[120:123], v[66:69], v[16:31]
	global_load_dwordx2 v[118:119], v[106:107], off offset:80
	global_load_dwordx2 v[120:121], v[106:107], off offset:96
	s_nop 0
	global_load_dwordx2 v[106:107], v[106:107], off offset:112
	s_nop 0
	global_load_dwordx2 v[122:123], v[104:105], off offset:64
	global_load_dwordx2 v[130:131], v[104:105], off offset:80
	global_load_dwordx2 v[186:187], v[104:105], off offset:96
	s_nop 0
	global_load_dwordx2 v[104:105], v[104:105], off offset:112
	s_nop 1
	v_pk_mul_f32 v[16:17], v[16:17], v[114:115] op_sel_hi:[1,0]
	s_waitcnt lgkmcnt(0)
	v_mfma_f32_32x32x16_bf16 v[0:15], v[76:79], v[66:69], v[0:15]
	global_load_dwordx4 v[76:79], v[64:65], off
	global_load_dwordx4 v[72:75], v[64:65], off offset:32
	global_load_dwordx4 v[68:71], v[64:65], off offset:64
	s_nop 0
	global_load_dwordx4 v[64:67], v[64:65], off offset:96
	v_fma_f32 v16, v112, v188, v16
	v_fma_f32 v17, v112, v189, v17
	s_waitcnt vmcnt(19)
; #define LAS __attribute__((address_space(3)))
; __device__ __forceinline__ float bf_lo(unsigned u) { return __uint_as_float(u << 16); }
; __device__ __forceinline__ float bf_hi(unsigned u) { return __uint_as_float(u & 0xffff0000u); }
; __device__ __forceinline__ void attn_stage(LAS unsigned char* lds, const u32x4 (&kv)[6], const u32x4 (&vv)[6], int tid, int wid) {
;     LAS unsigned char* Kl = lds; LAS unsigned char* Vl = lds + 49152;
; #pragma unroll
;     for (int c = 0; c < 6; ++c) { const int idx = tid + 512 * c, j = idx >> 3, ch = idx & 7;
;         *(LAS u32x4*)(Kl + j * 128 + ((ch ^ ((j >> 1) & 7)) * 16)) = kv[c];
;         *(LAS u32x4*)(Vl + j * 128 + (((ch >> 2) ^ ((j >> 1) & 1)) * 64) + (ch & 3) * 16) = vv[c]; }
; }
; template <bool FINAL>
; __device__ __forceinline__ void attn_compute(LAS unsigned char* lds, const bf16_t* proj, const AttnItem& t, const AttnItem& nxt, bool more, bf16x8 (&qf)[4], bf16_t* o23, float* lse23, bf16_t* ycat, int lane, int wid) {
;     ...
;         bf16_t* yo = ycat + qrow * DM + t.h * HD + 8 * hi;
; #pragma unroll
;         for (int d = 0; d < 2; ++d)
; #pragma unroll
;             for (int g = 0; g < 4; g += 2) { u32x2 wp[2];
; #pragma unroll
;                 for (int e = 0; e < 2; ++e) { const int gg = g + e; const u32x2 b2 = a2[4 * d + gg], b3 = a3[4 * d + gg];
;                     wp[e].x = cvt_pk_bf16(c1 * o[d][4 * gg] + c2 * bf_lo(b2.x) + c3 * bf_lo(b3.x), c1 * o[d][4 * gg + 1] + c2 * bf_hi(b2.x) + c3 * bf_hi(b3.x));
;                     wp[e].y = cvt_pk_bf16(c1 * o[d][4 * gg + 2] + c2 * bf_lo(b2.y) + c3 * bf_lo(b3.y), c1 * o[d][4 * gg + 3] + c2 * bf_hi(b2.y) + c3 * bf_hi(b3.y)); }
;                 *(u32x4*)(yo + 32 * d + 8 * g) = pair16(wp[0], wp[1]); }
	v_lshlrev_b32_e32 v188, 16, v204
	v_and_b32_e32 v189, 0xffff0000, v204
	v_pk_fma_f32 v[16:17], v[110:111], v[188:189], v[16:17] op_sel_hi:[0,1,1]
	v_pk_mul_f32 v[18:19], v[18:19], v[114:115] op_sel_hi:[1,0]
	v_lshlrev_b32_e32 v188, 16, v201
	v_and_b32_e32 v189, 0xffff0000, v201
	v_pk_fma_f32 v[18:19], v[112:113], v[188:189], v[18:19] op_sel_hi:[0,1,1]
	v_lshlrev_b32_e32 v188, 16, v205
	v_and_b32_e32 v189, 0xffff0000, v205
	v_pk_fma_f32 v[18:19], v[110:111], v[188:189], v[18:19] op_sel_hi:[0,1,1]
	v_cvt_pk_bf16_f32 v16, v16, v17
	v_cvt_pk_bf16_f32 v17, v18, v19
	v_pk_mul_f32 v[18:19], v[20:21], v[114:115] op_sel_hi:[1,0]
	v_lshlrev_b32_e32 v20, 16, v202
	v_and_b32_e32 v21, 0xffff0000, v202
	v_pk_fma_f32 v[18:19], v[112:113], v[20:21], v[18:19] op_sel_hi:[0,1,1]
	s_waitcnt vmcnt(18)
	v_lshlrev_b32_e32 v20, 16, v116
	v_and_b32_e32 v21, 0xffff0000, v116
	v_pk_fma_f32 v[18:19], v[110:111], v[20:21], v[18:19] op_sel_hi:[0,1,1]
	v_pk_mul_f32 v[20:21], v[22:23], v[114:115] op_sel_hi:[1,0]
	v_lshlrev_b32_e32 v22, 16, v203
	v_and_b32_e32 v23, 0xffff0000, v203
	v_pk_fma_f32 v[20:21], v[112:113], v[22:23], v[20:21] op_sel_hi:[0,1,1]
	v_lshlrev_b32_e32 v22, 16, v117
	v_and_b32_e32 v23, 0xffff0000, v117
	v_pk_fma_f32 v[20:21], v[110:111], v[22:23], v[20:21] op_sel_hi:[0,1,1]
	v_cvt_pk_bf16_f32 v18, v18, v19
	v_cvt_pk_bf16_f32 v19, v20, v21
	s_nop 0
	v_permlane32_swap_b32_e32 v16, v18
	v_permlane32_swap_b32_e32 v17, v19
	global_store_dwordx4 v[108:109], v[16:19], off
	s_waitcnt vmcnt(18)
	v_lshlrev_b32_e32 v20, 16, v133
	v_and_b32_e32 v21, 0xffff0000, v133
	v_pk_mul_f32 v[16:17], v[24:25], v[114:115] op_sel_hi:[1,0]
	v_lshlrev_b32_e32 v18, 16, v132
	v_and_b32_e32 v19, 0xffff0000, v132
	v_pk_fma_f32 v[16:17], v[112:113], v[18:19], v[16:17] op_sel_hi:[0,1,1]
	s_waitcnt vmcnt(17)
	v_lshlrev_b32_e32 v18, 16, v134
	v_and_b32_e32 v19, 0xffff0000, v134
	v_pk_fma_f32 v[16:17], v[110:111], v[18:19], v[16:17] op_sel_hi:[0,1,1]
	v_pk_mul_f32 v[18:19], v[26:27], v[114:115] op_sel_hi:[1,0]
	v_cvt_pk_bf16_f32 v16, v16, v17
	v_pk_fma_f32 v[18:19], v[112:113], v[20:21], v[18:19] op_sel_hi:[0,1,1]
	v_lshlrev_b32_e32 v20, 16, v135
	v_and_b32_e32 v21, 0xffff0000, v135
	v_pk_fma_f32 v[18:19], v[110:111], v[20:21], v[18:19] op_sel_hi:[0,1,1]
	v_cvt_pk_bf16_f32 v17, v18, v19
	v_pk_mul_f32 v[18:19], v[28:29], v[114:115] op_sel_hi:[1,0]
	s_waitcnt vmcnt(14)
	v_lshlrev_b32_e32 v20, 16, v124
	v_and_b32_e32 v21, 0xffff0000, v124
	v_pk_fma_f32 v[18:19], v[112:113], v[20:21], v[18:19] op_sel_hi:[0,1,1]
	s_waitcnt vmcnt(13)
	v_lshlrev_b32_e32 v20, 16, v126
	v_and_b32_e32 v21, 0xffff0000, v126
	v_pk_fma_f32 v[18:19], v[110:111], v[20:21], v[18:19] op_sel_hi:[0,1,1]
	v_pk_mul_f32 v[20:21], v[30:31], v[114:115] op_sel_hi:[1,0]
	v_lshlrev_b32_e32 v22, 16, v125
	v_and_b32_e32 v23, 0xffff0000, v125
	v_pk_fma_f32 v[20:21], v[112:113], v[22:23], v[20:21] op_sel_hi:[0,1,1]
	v_lshlrev_b32_e32 v22, 16, v127
	v_and_b32_e32 v23, 0xffff0000, v127
	v_pk_fma_f32 v[20:21], v[110:111], v[22:23], v[20:21] op_sel_hi:[0,1,1]
	v_cvt_pk_bf16_f32 v18, v18, v19
	v_cvt_pk_bf16_f32 v19, v20, v21
	s_nop 0
	v_permlane32_swap_b32_e32 v16, v18
	v_permlane32_swap_b32_e32 v17, v19
	global_store_dwordx4 v[108:109], v[16:19], off offset:32
	v_pk_mul_f32 v[0:1], v[0:1], v[114:115] op_sel_hi:[1,0]
	v_pk_mul_f32 v[2:3], v[2:3], v[114:115] op_sel_hi:[1,0]
	s_waitcnt vmcnt(13)
	v_lshlrev_b32_e32 v16, 16, v128
	v_and_b32_e32 v17, 0xffff0000, v128
	v_pk_fma_f32 v[0:1], v[112:113], v[16:17], v[0:1] op_sel_hi:[0,1,1]
	s_waitcnt vmcnt(9)
	v_lshlrev_b32_e32 v16, 16, v122
	v_and_b32_e32 v17, 0xffff0000, v122
	v_pk_fma_f32 v[0:1], v[110:111], v[16:17], v[0:1] op_sel_hi:[0,1,1]
	v_lshlrev_b32_e32 v16, 16, v129
	v_and_b32_e32 v17, 0xffff0000, v129
	v_pk_fma_f32 v[2:3], v[112:113], v[16:17], v[2:3] op_sel_hi:[0,1,1]
	v_lshlrev_b32_e32 v16, 16, v123
	v_and_b32_e32 v17, 0xffff0000, v123
	v_pk_fma_f32 v[2:3], v[110:111], v[16:17], v[2:3] op_sel_hi:[0,1,1]
	v_cvt_pk_bf16_f32 v0, v0, v1
	v_cvt_pk_bf16_f32 v1, v2, v3
	v_pk_mul_f32 v[2:3], v[4:5], v[114:115] op_sel_hi:[1,0]
	v_lshlrev_b32_e32 v4, 16, v118
	v_and_b32_e32 v5, 0xffff0000, v118
	v_pk_fma_f32 v[2:3], v[112:113], v[4:5], v[2:3] op_sel_hi:[0,1,1]
	s_waitcnt vmcnt(8)
	v_lshlrev_b32_e32 v4, 16, v130
	v_and_b32_e32 v5, 0xffff0000, v130
	v_pk_fma_f32 v[2:3], v[110:111], v[4:5], v[2:3] op_sel_hi:[0,1,1]
	v_pk_mul_f32 v[4:5], v[6:7], v[114:115] op_sel_hi:[1,0]
	v_lshlrev_b32_e32 v6, 16, v119
	v_and_b32_e32 v7, 0xffff0000, v119
	v_pk_fma_f32 v[4:5], v[112:113], v[6:7], v[4:5] op_sel_hi:[0,1,1]
	v_lshlrev_b32_e32 v6, 16, v131
	v_and_b32_e32 v7, 0xffff0000, v131
	v_pk_fma_f32 v[4:5], v[110:111], v[6:7], v[4:5] op_sel_hi:[0,1,1]
	v_cvt_pk_bf16_f32 v2, v2, v3
	v_cvt_pk_bf16_f32 v3, v4, v5
	s_nop 0
	v_permlane32_swap_b32_e32 v0, v2
	v_permlane32_swap_b32_e32 v1, v3
	global_store_dwordx4 v[108:109], v[0:3], off offset:64
	v_lshlrev_b32_e32 v4, 16, v121
	v_and_b32_e32 v5, 0xffff0000, v121
	v_pk_mul_f32 v[0:1], v[8:9], v[114:115] op_sel_hi:[1,0]
	v_lshlrev_b32_e32 v2, 16, v120
	v_and_b32_e32 v3, 0xffff0000, v120
	v_pk_fma_f32 v[0:1], v[112:113], v[2:3], v[0:1] op_sel_hi:[0,1,1]
	s_waitcnt vmcnt(8)
	v_lshlrev_b32_e32 v2, 16, v186
	v_and_b32_e32 v3, 0xffff0000, v186
	v_pk_fma_f32 v[0:1], v[110:111], v[2:3], v[0:1] op_sel_hi:[0,1,1]
	v_pk_mul_f32 v[2:3], v[10:11], v[114:115] op_sel_hi:[1,0]
	v_cvt_pk_bf16_f32 v0, v0, v1
	v_pk_fma_f32 v[2:3], v[112:113], v[4:5], v[2:3] op_sel_hi:[0,1,1]
	v_lshlrev_b32_e32 v4, 16, v187
	v_and_b32_e32 v5, 0xffff0000, v187
	v_pk_fma_f32 v[2:3], v[110:111], v[4:5], v[2:3] op_sel_hi:[0,1,1]
	v_cvt_pk_bf16_f32 v1, v2, v3
	v_pk_mul_f32 v[2:3], v[12:13], v[114:115] op_sel_hi:[1,0]
	v_lshlrev_b32_e32 v4, 16, v106
	v_and_b32_e32 v5, 0xffff0000, v106
	v_pk_fma_f32 v[2:3], v[112:113], v[4:5], v[2:3] op_sel_hi:[0,1,1]
	s_waitcnt vmcnt(7)
	v_lshlrev_b32_e32 v4, 16, v104
	v_and_b32_e32 v5, 0xffff0000, v104
	v_pk_fma_f32 v[2:3], v[110:111], v[4:5], v[2:3] op_sel_hi:[0,1,1]
	v_pk_mul_f32 v[4:5], v[14:15], v[114:115] op_sel_hi:[1,0]
	v_lshlrev_b32_e32 v6, 16, v107
	v_and_b32_e32 v7, 0xffff0000, v107
	v_pk_fma_f32 v[4:5], v[112:113], v[6:7], v[4:5] op_sel_hi:[0,1,1]
	v_lshlrev_b32_e32 v6, 16, v105
	v_and_b32_e32 v7, 0xffff0000, v105
	v_pk_fma_f32 v[4:5], v[110:111], v[6:7], v[4:5] op_sel_hi:[0,1,1]
	v_cvt_pk_bf16_f32 v2, v2, v3
	v_cvt_pk_bf16_f32 v3, v4, v5
	s_nop 0
	v_permlane32_swap_b32_e32 v0, v2
	v_permlane32_swap_b32_e32 v1, v3
	global_store_dwordx4 v[108:109], v[0:3], off offset:96
	s_waitcnt lgkmcnt(0)
	s_barrier
	s_cbranch_scc0 .LBB0_480
	ds_write_b128 v158, v[32:35]
	ds_write_b128 v159, v[36:39] offset:49152
	ds_write_b128 v160, v[40:43]
	ds_write_b128 v161, v[44:47] offset:49152
	ds_write_b128 v162, v[48:51]
	ds_write_b128 v163, v[52:55] offset:49152
	ds_write_b128 v164, v[56:59]
	ds_write_b128 v165, v[60:63] offset:49152
	ds_write_b128 v166, v[80:83]
	ds_write_b128 v167, v[84:87] offset:49152
	ds_write_b128 v183, v[88:91]
	ds_write_b128 v185, v[92:95] offset:49152
	s_branch .Lattn_b_ldone

; template <bool FINAL>
; __device__ __forceinline__ void attn_phase(LAS unsigned char* lds, const bf16_t* proj, bf16_t* o23, float* lse23, bf16_t* ycat, int tid, int lane, int wid) {
;     ...
;     const int SPB = affine ? RB / J : 1, NS = affine ? 4 * SPB : (NR - (int)blockIdx.x + G - 1) / G;
;     auto round_of = [&](int t) -> int {
;         if (!affine) return (int)blockIdx.x + t * G;
;         const int sidx = t / SPB, rr = jj + J * (t % SPB), bh = 4 * xcd + sidx;
;         return FINAL ? bh * 32 + rr : (rr >> 5) * 1024 + bh * 32 + (rr & 31); };
;     ...
;         asm volatile("s_waitcnt lgkmcnt(0)\n\ts_barrier" ::: "memory");
;         const bool more = t + 1 < NS;
;         const AttnItem nxt = attn_decode<FINAL>(round_of(more ? t + 1 : t), wid);
.Lattn_b_ldone:
	s_mov_b32 s10, s17
	s_waitcnt lgkmcnt(0)
	s_barrier
	s_add_i32 s17, s17, 1
	v_readlane_b32 s20, v251, 63
	s_cmp_lt_i32 s17, s15
	v_readlane_b32 s21, v250, 0
	s_cselect_b32 s10, s17, s10
	s_andn2_b64 vcc, exec, s[20:21]
	s_mov_b64 s[24:25], -1
	s_cbranch_vccnz .LBB0_477
	s_mul_i32 s14, s10, s30
	v_readlane_b32 s19, v251, 42
	s_add_i32 s14, s14, s19
	s_mov_b64 s[24:25], 0
